# S5 scan loops: B*u block transposed to lane=state with v_permlane32_swap/v_permlane16_swap instead of an LDS write/read round trip; bit-identical
# speedup vs baseline: 1.0043x; 1.0043x over previous
; #define LAS __attribute__((address_space(3)))
; __device__ __forceinline__ unsigned pk2(float lo, float hi) { f32x2 v = {lo, hi}; bf16x2_t b = __builtin_convertvector(v, bf16x2_t); return __builtin_bit_cast(unsigned, b); }
; __device__ __forceinline__ void s5_unit(LAS unsigned char* lds, const Params& P, int l, int b, int g, const bf16_t* ub, bf16_t* y2) {
;     ...
;         for (int sc = 0; sc < 16; ++sc) {
;             const u32x4 uw = uw_n; const u32x2 uu_c = uu_n;
;             if (sc < 15) {
;                 if (kq < 2) uw_n = *(const u32x4*)(ub + (row0 + 16 * (sc + 1) + c15) * 256 + g * 16 + 8 * kq);
;                 if (0) uu_n = *(const u32x2*)(ub + (row0 + 16 * (sc + 1) + c15) * 256 + g * 16 + 4 * kq);
;             }
;             const bf16x8 uf = __builtin_bit_cast(bf16x8, uw);
; #pragma unroll
;             for (int nb = 0; nb < 8; ++nb) {
;                 const f32x4 d = __builtin_amdgcn_mfma_f32_16x16x32_bf16(uf, bfr[nb], (f32x4){0.f, 0.f, 0.f, 0.f}, 0, 0, 0);
;                 *(LAS f32x4*)(BUs + (16 * nb + c15) * 20 + 4 * kq) = d;
;             }
;             asm volatile("s_waitcnt lgkmcnt(0)" ::: "memory");
;             f32x4 bre4[4], bim4[4];
; #pragma unroll
;             for (int q = 0; q < 4; ++q) { bre4[q] = *(const LAS f32x4*)(BUs + lane * 20 + 4 * q); bim4[q] = *(const LAS f32x4*)(BUs + (64 + lane) * 20 + 4 * q); }
; #pragma unroll
;             for (int tt = 0; tt < 16; ++tt) {
;                 const float bre = bre4[tt >> 2][tt & 3], bim = bim4[tt >> 2][tt & 3];
;                 const float nxr = lbr * xr - lbi * xi + bre, nxi = lbr * xi + lbi * xr + bim; xr = nxr; xi = nxi;
;                 if (0) *(LAS unsigned*)(Xs + tt * 272 + lane * 4) = pk2(xr, xi);
;             }
.LBB0_608:
	s_or_b64 exec, exec, s[8:9]
	v_mfma_f32_16x16x32_bf16 v[140:143], v[76:79], v[12:15], 0
	v_mfma_f32_16x16x32_bf16 v[144:147], v[76:79], v[20:23], 0
	v_mfma_f32_16x16x32_bf16 v[148:151], v[76:79], v[28:31], 0
	v_mfma_f32_16x16x32_bf16 v[152:155], v[76:79], v[36:39], 0
	v_mfma_f32_16x16x32_bf16 v[156:159], v[76:79], v[8:11], 0
	v_mfma_f32_16x16x32_bf16 v[160:163], v[76:79], v[16:19], 0
	v_mfma_f32_16x16x32_bf16 v[164:167], v[76:79], v[24:27], 0
	v_mfma_f32_16x16x32_bf16 v[168:171], v[76:79], v[32:35], 0
	s_add_u32 s12, s12, 0x2000
	s_addc_u32 s13, s13, 0
	s_cmp_eq_u32 s12, 0x20000
	s_nop 3
	v_permlane32_swap_b32_e32 v140, v148
	v_permlane32_swap_b32_e32 v144, v152
	v_permlane32_swap_b32_e32 v141, v149
	v_permlane32_swap_b32_e32 v145, v153
	v_permlane32_swap_b32_e32 v142, v150
	v_permlane32_swap_b32_e32 v146, v154
	v_permlane32_swap_b32_e32 v143, v151
	v_permlane32_swap_b32_e32 v147, v155
	v_permlane16_swap_b32_e32 v140, v144
	v_permlane16_swap_b32_e32 v148, v152
	v_permlane16_swap_b32_e32 v141, v145
	v_permlane16_swap_b32_e32 v149, v153
	v_permlane16_swap_b32_e32 v142, v146
	v_permlane16_swap_b32_e32 v150, v154
	v_permlane16_swap_b32_e32 v143, v147
	v_permlane16_swap_b32_e32 v151, v155
	v_permlane32_swap_b32_e32 v156, v164
	v_permlane32_swap_b32_e32 v160, v168
	v_permlane32_swap_b32_e32 v157, v165
	v_permlane32_swap_b32_e32 v161, v169
	v_permlane32_swap_b32_e32 v158, v166
	v_permlane32_swap_b32_e32 v162, v170
	v_permlane32_swap_b32_e32 v159, v167
	v_permlane32_swap_b32_e32 v163, v171
	v_permlane16_swap_b32_e32 v156, v160
	v_permlane16_swap_b32_e32 v164, v168
	v_permlane16_swap_b32_e32 v157, v161
	v_permlane16_swap_b32_e32 v165, v169
	v_permlane16_swap_b32_e32 v158, v162
	v_permlane16_swap_b32_e32 v166, v170
	v_permlane16_swap_b32_e32 v159, v163
	v_permlane16_swap_b32_e32 v167, v171
	v_fma_f32 v136, -v84, v99, v140
	v_fma_f32 v137, v84, v98, v156
	v_fma_f32 v98, v2, v98, v136
	v_fma_f32 v99, v2, v99, v137
	v_fma_f32 v136, -v84, v99, v141
	v_fma_f32 v137, v84, v98, v157
	v_fma_f32 v98, v2, v98, v136
	v_fma_f32 v99, v2, v99, v137
	v_fma_f32 v136, -v84, v99, v142
	v_fma_f32 v137, v84, v98, v158
	v_fma_f32 v98, v2, v98, v136
	v_fma_f32 v99, v2, v99, v137
	v_fma_f32 v136, -v84, v99, v143
	v_fma_f32 v137, v84, v98, v159
	v_fma_f32 v98, v2, v98, v136
	v_fma_f32 v99, v2, v99, v137
	v_fma_f32 v136, -v84, v99, v144
	v_fma_f32 v137, v84, v98, v160
	v_fma_f32 v98, v2, v98, v136
	v_fma_f32 v99, v2, v99, v137
	v_fma_f32 v136, -v84, v99, v145
	v_fma_f32 v137, v84, v98, v161
	v_fma_f32 v98, v2, v98, v136
	v_fma_f32 v99, v2, v99, v137
	v_fma_f32 v136, -v84, v99, v146
	v_fma_f32 v137, v84, v98, v162
	v_fma_f32 v98, v2, v98, v136
	v_fma_f32 v99, v2, v99, v137
	v_fma_f32 v136, -v84, v99, v147
	v_fma_f32 v137, v84, v98, v163
	v_fma_f32 v98, v2, v98, v136
	v_fma_f32 v99, v2, v99, v137
	v_fma_f32 v136, -v84, v99, v148
	v_fma_f32 v137, v84, v98, v164
	v_fma_f32 v98, v2, v98, v136
	v_fma_f32 v99, v2, v99, v137
	v_fma_f32 v136, -v84, v99, v149
	v_fma_f32 v137, v84, v98, v165
	v_fma_f32 v98, v2, v98, v136
	v_fma_f32 v99, v2, v99, v137
	v_fma_f32 v136, -v84, v99, v150
	v_fma_f32 v137, v84, v98, v166
	v_fma_f32 v98, v2, v98, v136
	v_fma_f32 v99, v2, v99, v137
	v_fma_f32 v136, -v84, v99, v151
	v_fma_f32 v137, v84, v98, v167
	v_fma_f32 v98, v2, v98, v136
	v_fma_f32 v99, v2, v99, v137
	v_fma_f32 v136, -v84, v99, v152
	v_fma_f32 v137, v84, v98, v168
	v_fma_f32 v98, v2, v98, v136
	v_fma_f32 v99, v2, v99, v137
	v_fma_f32 v136, -v84, v99, v153
	v_fma_f32 v137, v84, v98, v169
	v_fma_f32 v98, v2, v98, v136
	v_fma_f32 v99, v2, v99, v137
	v_fma_f32 v136, -v84, v99, v154
	v_fma_f32 v137, v84, v98, v170
	v_fma_f32 v98, v2, v98, v136
	v_fma_f32 v99, v2, v99, v137
	v_fma_f32 v136, -v84, v99, v155
	v_fma_f32 v137, v84, v98, v171
	v_fma_f32 v98, v2, v98, v136
	v_fma_f32 v99, v2, v99, v137
	s_waitcnt vmcnt(0)
	v_mov_b64_e32 v[78:79], v[74:75]
	v_mov_b64_e32 v[76:77], v[72:73]
	s_cbranch_scc1 .LBB0_611

; #define LAS __attribute__((address_space(3)))
; __device__ __forceinline__ unsigned pk2(float lo, float hi) { f32x2 v = {lo, hi}; bf16x2_t b = __builtin_convertvector(v, bf16x2_t); return __builtin_bit_cast(unsigned, b); }
; __device__ __forceinline__ void s5_unit(LAS unsigned char* lds, const Params& P, int l, int b, int g, const bf16_t* ub, bf16_t* y2) {
;     ...
;         for (int sc = 0; sc < 16; ++sc) {
;             const u32x4 uw = uw_n; const u32x2 uu_c = uu_n;
;             if (sc < 15) {
;                 if (kq < 2) uw_n = *(const u32x4*)(ub + (row0 + 16 * (sc + 1) + c15) * 256 + g * 16 + 8 * kq);
;                 if (1) uu_n = *(const u32x2*)(ub + (row0 + 16 * (sc + 1) + c15) * 256 + g * 16 + 4 * kq);
;             }
;             const bf16x8 uf = __builtin_bit_cast(bf16x8, uw);
; #pragma unroll
;             for (int nb = 0; nb < 8; ++nb) {
;                 const f32x4 d = __builtin_amdgcn_mfma_f32_16x16x32_bf16(uf, bfr[nb], (f32x4){0.f, 0.f, 0.f, 0.f}, 0, 0, 0);
;                 *(LAS f32x4*)(BUs + (16 * nb + c15) * 20 + 4 * kq) = d;
;             }
;             asm volatile("s_waitcnt lgkmcnt(0)" ::: "memory");
;             f32x4 bre4[4], bim4[4];
; #pragma unroll
;             for (int q = 0; q < 4; ++q) { bre4[q] = *(const LAS f32x4*)(BUs + lane * 20 + 4 * q); bim4[q] = *(const LAS f32x4*)(BUs + (64 + lane) * 20 + 4 * q); }
; #pragma unroll
;             for (int tt = 0; tt < 16; ++tt) {
;                 const float bre = bre4[tt >> 2][tt & 3], bim = bim4[tt >> 2][tt & 3];
;                 const float nxr = lbr * xr - lbi * xi + bre, nxi = lbr * xi + lbi * xr + bim; xr = nxr; xi = nxi;
;                 if (1) *(LAS unsigned*)(Xs + tt * 272 + lane * 4) = pk2(xr, xi);
;             }
.LBB0_619:
	v_mfma_f32_16x16x32_bf16 v[140:143], v[72:75], v[12:15], 0
	v_mfma_f32_16x16x32_bf16 v[144:147], v[72:75], v[20:23], 0
	v_mfma_f32_16x16x32_bf16 v[148:151], v[72:75], v[28:31], 0
	v_mfma_f32_16x16x32_bf16 v[152:155], v[72:75], v[36:39], 0
	v_mfma_f32_16x16x32_bf16 v[156:159], v[72:75], v[8:11], 0
	v_mfma_f32_16x16x32_bf16 v[160:163], v[72:75], v[16:19], 0
	v_mfma_f32_16x16x32_bf16 v[164:167], v[72:75], v[24:27], 0
	v_mfma_f32_16x16x32_bf16 v[168:171], v[72:75], v[32:35], 0
	s_add_u32 s14, s14, 16
	s_addc_u32 s15, s15, 0
	s_add_u32 s12, s12, 0x2000
	s_addc_u32 s13, s13, 0
	s_cmp_lg_u32 s12, 0x20000
	s_nop 3
	v_permlane32_swap_b32_e32 v140, v148
	v_permlane32_swap_b32_e32 v144, v152
	v_permlane32_swap_b32_e32 v141, v149
	v_permlane32_swap_b32_e32 v145, v153
	v_permlane32_swap_b32_e32 v142, v150
	v_permlane32_swap_b32_e32 v146, v154
	v_permlane32_swap_b32_e32 v143, v151
	v_permlane32_swap_b32_e32 v147, v155
	v_permlane16_swap_b32_e32 v140, v144
	v_permlane16_swap_b32_e32 v148, v152
	v_permlane16_swap_b32_e32 v141, v145
	v_permlane16_swap_b32_e32 v149, v153
	v_permlane16_swap_b32_e32 v142, v146
	v_permlane16_swap_b32_e32 v150, v154
	v_permlane16_swap_b32_e32 v143, v147
	v_permlane16_swap_b32_e32 v151, v155
	v_permlane32_swap_b32_e32 v156, v164
	v_permlane32_swap_b32_e32 v160, v168
	v_permlane32_swap_b32_e32 v157, v165
	v_permlane32_swap_b32_e32 v161, v169
	v_permlane32_swap_b32_e32 v158, v166
	v_permlane32_swap_b32_e32 v162, v170
	v_permlane32_swap_b32_e32 v159, v167
	v_permlane32_swap_b32_e32 v163, v171
	v_permlane16_swap_b32_e32 v156, v160
	v_permlane16_swap_b32_e32 v164, v168
	v_permlane16_swap_b32_e32 v157, v161
	v_permlane16_swap_b32_e32 v165, v169
	v_permlane16_swap_b32_e32 v158, v162
	v_permlane16_swap_b32_e32 v166, v170
	v_permlane16_swap_b32_e32 v159, v163
	v_permlane16_swap_b32_e32 v167, v171
	v_add_u32_e32 v81, 0x2800, v68
	v_fma_f32 v74, -v84, v77, v140
	v_fma_f32 v75, v84, v76, v156
	v_fma_f32 v76, v2, v76, v74
	v_fma_f32 v77, v2, v77, v75
	v_cvt_pk_bf16_f32 v69, v76, v77
	v_fma_f32 v74, -v84, v77, v141
	v_fma_f32 v75, v84, v76, v157
	v_fma_f32 v76, v2, v76, v74
	v_fma_f32 v77, v2, v77, v75
	v_cvt_pk_bf16_f32 v80, v76, v77
	ds_write2_b32 v81, v69, v80 offset1:68
	v_fma_f32 v74, -v84, v77, v142
	v_fma_f32 v75, v84, v76, v158
	v_fma_f32 v76, v2, v76, v74
	v_fma_f32 v77, v2, v77, v75
	v_cvt_pk_bf16_f32 v69, v76, v77
	v_fma_f32 v74, -v84, v77, v143
	v_fma_f32 v75, v84, v76, v159
	v_fma_f32 v76, v2, v76, v74
	v_fma_f32 v77, v2, v77, v75
	v_cvt_pk_bf16_f32 v80, v76, v77
	ds_write2_b32 v81, v69, v80 offset0:136 offset1:204
	v_add_u32_e32 v81, 0x2c40, v68
	v_fma_f32 v74, -v84, v77, v144
	v_fma_f32 v75, v84, v76, v160
	v_fma_f32 v76, v2, v76, v74
	v_fma_f32 v77, v2, v77, v75
	v_cvt_pk_bf16_f32 v69, v76, v77
	v_fma_f32 v74, -v84, v77, v145
	v_fma_f32 v75, v84, v76, v161
	v_fma_f32 v76, v2, v76, v74
	v_fma_f32 v77, v2, v77, v75
	v_cvt_pk_bf16_f32 v80, v76, v77
	ds_write2_b32 v81, v69, v80 offset1:68
	v_fma_f32 v74, -v84, v77, v146
	v_fma_f32 v75, v84, v76, v162
	v_fma_f32 v76, v2, v76, v74
	v_fma_f32 v77, v2, v77, v75
	v_cvt_pk_bf16_f32 v69, v76, v77
	v_fma_f32 v74, -v84, v77, v147
	v_fma_f32 v75, v84, v76, v163
	v_fma_f32 v76, v2, v76, v74
	v_fma_f32 v77, v2, v77, v75
	v_cvt_pk_bf16_f32 v80, v76, v77
	ds_write2_b32 v81, v69, v80 offset0:136 offset1:204
	v_add_u32_e32 v81, 0x3080, v68
	v_fma_f32 v74, -v84, v77, v148
	v_fma_f32 v75, v84, v76, v164
	v_fma_f32 v76, v2, v76, v74
	v_fma_f32 v77, v2, v77, v75
	v_cvt_pk_bf16_f32 v69, v76, v77
	v_fma_f32 v74, -v84, v77, v149
	v_fma_f32 v75, v84, v76, v165
	v_fma_f32 v76, v2, v76, v74
	v_fma_f32 v77, v2, v77, v75
	v_cvt_pk_bf16_f32 v80, v76, v77
	ds_write2_b32 v81, v69, v80 offset1:68
	v_fma_f32 v74, -v84, v77, v150
	v_fma_f32 v75, v84, v76, v166
	v_fma_f32 v76, v2, v76, v74
	v_fma_f32 v77, v2, v77, v75
	v_cvt_pk_bf16_f32 v69, v76, v77
	v_fma_f32 v74, -v84, v77, v151
	v_fma_f32 v75, v84, v76, v167
	v_fma_f32 v76, v2, v76, v74
	v_fma_f32 v77, v2, v77, v75
	v_cvt_pk_bf16_f32 v80, v76, v77
	ds_write2_b32 v81, v69, v80 offset0:136 offset1:204
	v_add_u32_e32 v81, 0x34c0, v68
	v_fma_f32 v74, -v84, v77, v152
	v_fma_f32 v75, v84, v76, v168
	v_fma_f32 v76, v2, v76, v74
	v_fma_f32 v77, v2, v77, v75
	v_cvt_pk_bf16_f32 v69, v76, v77
	v_fma_f32 v74, -v84, v77, v153
	v_fma_f32 v75, v84, v76, v169
	v_fma_f32 v76, v2, v76, v74
	v_fma_f32 v77, v2, v77, v75
	v_cvt_pk_bf16_f32 v80, v76, v77
	ds_write2_b32 v81, v69, v80 offset1:68
	v_fma_f32 v74, -v84, v77, v154
	v_fma_f32 v75, v84, v76, v170
	v_fma_f32 v76, v2, v76, v74
	v_fma_f32 v77, v2, v77, v75
	v_cvt_pk_bf16_f32 v69, v76, v77
	v_fma_f32 v74, -v84, v77, v155
	v_fma_f32 v75, v84, v76, v171
	v_fma_f32 v76, v2, v76, v74
	v_fma_f32 v77, v2, v77, v75
	v_cvt_pk_bf16_f32 v80, v76, v77
	ds_write2_b32 v81, v69, v80 offset0:136 offset1:204
	v_lshlrev_b32_e32 v74, 16, v78
	s_waitcnt lgkmcnt(0)
; #define LAS __attribute__((address_space(3)))
; __device__ __forceinline__ void store4(bf16_t* p, f32x4 v) { u32x2 w; w.x = pk2(v.x, v.y); w.y = pk2(v.z, v.w); *(u32x2*)p = w; }
; __device__ __forceinline__ void s5_unit(LAS unsigned char* lds, const Params& P, int l, int b, int g, const bf16_t* ub, bf16_t* y2) {
;     ...
;             if (1) {
;                 f32x4 ya = (f32x4){0.f, 0.f, 0.f, 0.f};
; #pragma unroll
;                 for (int ks = 0; ks < 4; ++ks) { const bf16x8 a = *(const LAS bf16x8*)(Xs + c15 * 272 + (32 * ks + 8 * kq) * 2); ya = __builtin_amdgcn_mfma_f32_16x16x32_bf16(cfrg[ks], a, ya, 0, 0, 0); }
; { const long row = row0 + 16 * sc + c15; f32x4 o;
;                   const f32x4 uu = (f32x4){__uint_as_float(uu_c.x << 16), __uint_as_float(uu_c.x & 0xffff0000u), __uint_as_float(uu_c.y << 16), __uint_as_float(uu_c.y & 0xffff0000u)};
; #pragma unroll
;                   for (int e = 0; e < 4; ++e) { const float y = ya[e] + dh4[e] * uu[e]; const float z = 0.7978845608028654f * (y + 0.044715f * y * y * y);
;                       const float th = 1.f - 2.f * __builtin_amdgcn_rcpf(1.f + __builtin_amdgcn_exp2f(2.f * LOG2E * z)); o[e] = 0.5f * y * (1.f + th); }
;                   store4(y2 + row * 256 + g * 16 + 4 * kq, o); }
;                 asm volatile("s_waitcnt lgkmcnt(0)" ::: "memory");
;             }
	ds_read_b128 v[70:73], v0 offset:10240
	ds_read_b128 v[86:89], v0 offset:10304
	s_waitcnt lgkmcnt(1)
	v_mfma_f32_16x16x32_bf16 v[70:73], v[52:55], v[70:73], 0
	v_and_b32_e32 v75, 0xffff0000, v78
	v_lshlrev_b32_e32 v78, 16, v79
	v_and_b32_e32 v79, 0xffff0000, v79
	s_waitcnt lgkmcnt(0)
	v_mfma_f32_16x16x32_bf16 v[70:73], v[48:51], v[86:89], v[70:73]
	ds_read_b128 v[86:89], v0 offset:10368
	ds_read_b128 v[90:93], v0 offset:10432
	s_waitcnt lgkmcnt(1)
	v_mfma_f32_16x16x32_bf16 v[70:73], v[44:47], v[86:89], v[70:73]
	s_waitcnt lgkmcnt(0)
	v_mfma_f32_16x16x32_bf16 v[70:73], v[40:43], v[90:93], v[70:73]
	s_nop 7
	v_pk_fma_f32 v[70:71], v[4:5], v[74:75], v[70:71]
	v_pk_fma_f32 v[72:73], v[6:7], v[78:79], v[72:73]
	v_mul_f32_e32 v69, 0x3d372713, v70
	v_mul_f32_e32 v69, v70, v69
	v_mul_f32_e32 v74, 0x3d372713, v71
	v_fma_f32 v69, v70, v69, v70
	v_mul_f32_e32 v74, v71, v74
	v_mul_f32_e32 v69, 0x3f4c422a, v69
	v_fma_f32 v74, v71, v74, v71
	v_mul_f32_e32 v69, 0x4038aa3b, v69
	v_mul_f32_e32 v74, 0x3f4c422a, v74
	v_exp_f32_e32 v69, v69
	v_mul_f32_e32 v74, 0x4038aa3b, v74
	v_exp_f32_e32 v75, v74
	v_mul_f32_e32 v78, 0x3d372713, v73
	v_add_f32_e32 v69, 1.0, v69
	v_rcp_f32_e32 v74, v69
	v_add_f32_e32 v69, 1.0, v75
	v_rcp_f32_e32 v75, v69
	v_mul_f32_e32 v69, 0x3d372713, v72
	v_mul_f32_e32 v69, v72, v69
	v_fma_f32 v69, v72, v69, v72
	v_mul_f32_e32 v78, v73, v78
	v_mul_f32_e32 v69, 0x3f4c422a, v69
	v_fma_f32 v78, v73, v78, v73
	v_mul_f32_e32 v69, 0x4038aa3b, v69
	v_mul_f32_e32 v78, 0x3f4c422a, v78
	v_exp_f32_e32 v69, v69
	v_mul_f32_e32 v78, 0x4038aa3b, v78
	v_exp_f32_e32 v79, v78
	v_pk_fma_f32 v[74:75], v[74:75], 2.0, 1.0 op_sel_hi:[1,0,0] neg_lo:[1,0,0] neg_hi:[1,0,0]
	v_add_f32_e32 v69, 1.0, v69
	v_rcp_f32_e32 v78, v69
	v_add_f32_e32 v69, 1.0, v79
	v_rcp_f32_e32 v79, v69
	v_pk_mul_f32 v[70:71], v[70:71], 0.5 op_sel_hi:[1,0]
	v_pk_add_f32 v[74:75], v[74:75], 1.0 op_sel_hi:[1,0]
	v_pk_mul_f32 v[72:73], v[72:73], 0.5 op_sel_hi:[1,0]
	v_pk_mul_f32 v[70:71], v[70:71], v[74:75]
	v_pk_fma_f32 v[74:75], v[78:79], 2.0, 1.0 op_sel_hi:[1,0,0] neg_lo:[1,0,0] neg_hi:[1,0,0]
	v_cvt_pk_bf16_f32 v70, v70, v71
	v_pk_add_f32 v[74:75], v[74:75], 1.0 op_sel_hi:[1,0]
	s_waitcnt vmcnt(0)
	v_mov_b64_e32 v[78:79], v[66:67]
	v_pk_mul_f32 v[72:73], v[72:73], v[74:75]
	v_or_b32_e32 v75, s17, v83
	v_or_b32_e32 v74, s16, v82
	v_lshlrev_b64 v[74:75], 9, v[74:75]
	v_lshl_add_u64 v[74:75], v[60:61], 0, v[74:75]
	v_cvt_pk_bf16_f32 v71, v72, v73
	global_store_dwordx2 v[74:75], v[70:71], off
	s_waitcnt lgkmcnt(0)
	v_mov_b64_e32 v[74:75], v[58:59]
	v_mov_b64_e32 v[72:73], v[56:57]
	s_cbranch_scc0 .LBB0_564
